# attention staging (second body): SGPR copy removed, s71 used directly (on top of v19)
# baseline (speedup 1.0000x reference)
.LBB0_685:
	s_mulk_i32 s71, 0x3400
	s_xor_b32 s2, s69, 2
	v_add_u32_e32 v0, s71, v192
	s_mulk_i32 s2, 0x2400
	s_waitcnt vmcnt(3)
	ds_write_b128 v0, v[168:171]
	v_add_u32_e32 v0, s71, v185
	ds_write_b128 v0, v[164:167] offset:128
	v_add_u32_e32 v0, s2, v193
	s_add_i32 s2, s67, 6
	s_min_i32 s2, s2, s66
	s_mov_b32 s3, s47
	v_add_u32_e32 v0, 0xd000, v0
	s_lshl_b64 s[4:5], s[2:3], 16
	s_lshl_b64 s[2:3], s[2:3], 12
	ds_write2_b64 v0, v[160:161], v[162:163] offset1:2
	v_lshl_add_u64 v[2:3], v[186:187], 0, s[4:5]
	v_lshl_add_u64 v[4:5], v[188:189], 0, s[2:3]
	s_lshl_b64 s[2:3], s[46:47], 7
	global_load_dwordx4 v[168:171], v[2:3], off
	global_load_dwordx4 v[164:167], v[4:5], off
	v_lshl_add_u64 v[2:3], v[190:191], 0, s[2:3]
	global_load_dwordx4 v[160:163], v[2:3], off
	s_add_i32 s46, s67, 2
	s_cmp_ge_i32 s67, s65
	s_cbranch_scc1 .LBB0_696
	s_and_b32 s2, s46, 2
	s_mulk_i32 s2, 0x3400
	v_add_u32_e32 v0, s2, v196
	ds_read_b128 v[2:5], v0
	ds_read_b128 v[6:9], v0 offset:6656
	s_waitcnt lgkmcnt(1)
	v_mfma_f32_32x32x16_bf16 v[112:127], v[2:5], v[128:131], v[48:63]
	ds_read_b128 v[10:13], v0 offset:32
	ds_read_b128 v[202:205], v0 offset:6688
	v_add_f32_e32 v14, 0, v80
	v_add_f32_e32 v14, v81, v14
	v_cvt_pk_bf16_f32 v176, v80, v81
	s_waitcnt lgkmcnt(2)
	v_mfma_f32_32x32x16_bf16 v[96:111], v[6:9], v[128:131], v[48:63]
	v_add_f32_e32 v2, v82, v14
	v_add_f32_e32 v2, v83, v2
	v_add_f32_e32 v14, v84, v2
	v_cvt_pk_bf16_f32 v177, v82, v83
	s_waitcnt lgkmcnt(1)
	v_mfma_f32_32x32x16_bf16 v[112:127], v[10:13], v[132:135], v[112:127]
	ds_read_b128 v[2:5], v0 offset:64
	ds_read_b128 v[6:9], v0 offset:6720
	v_add_f32_e32 v14, v85, v14
	v_add_f32_e32 v14, v86, v14
	v_add_f32_e32 v14, v87, v14
	v_cvt_pk_bf16_f32 v178, v84, v85
	v_cvt_pk_bf16_f32 v179, v86, v87
	s_waitcnt lgkmcnt(2)
	v_mfma_f32_32x32x16_bf16 v[96:111], v[202:205], v[132:135], v[96:111]
	v_add_f32_e32 v10, v88, v14
	v_add_f32_e32 v11, v89, v10
	v_cvt_pk_bf16_f32 v10, v88, v89
	s_waitcnt lgkmcnt(1)
	v_mfma_f32_32x32x16_bf16 v[112:127], v[2:5], v[136:139], v[112:127]
	ds_read_b128 v[80:83], v0 offset:96
	ds_read_b128 v[202:205], v0 offset:6752
	v_add_f32_e32 v11, v90, v11
	v_add_f32_e32 v11, v91, v11
	v_add_f32_e32 v12, v92, v11
	v_cvt_pk_bf16_f32 v11, v90, v91
	s_waitcnt lgkmcnt(2)
	v_mfma_f32_32x32x16_bf16 v[96:111], v[6:9], v[136:139], v[96:111]
	v_add_f32_e32 v2, v93, v12
	v_add_f32_e32 v2, v94, v2
	v_add_f32_e32 v14, v95, v2
	v_cvt_pk_bf16_f32 v12, v92, v93
	v_cvt_pk_bf16_f32 v13, v94, v95
	s_waitcnt lgkmcnt(1)
	v_mfma_f32_32x32x16_bf16 v[112:127], v[80:83], v[140:143], v[112:127]
	ds_read_b128 v[2:5], v0 offset:128
	ds_read_b128 v[206:209], v0 offset:6784
	v_add_f32_e32 v6, v16, v14
	v_add_f32_e32 v7, v17, v6
	v_cvt_pk_bf16_f32 v6, v16, v17
	s_waitcnt lgkmcnt(2)
	v_mfma_f32_32x32x16_bf16 v[96:111], v[202:205], v[140:143], v[96:111]
	v_add_f32_e32 v7, v18, v7
	v_add_f32_e32 v7, v19, v7
	v_add_f32_e32 v8, v20, v7
	v_cvt_pk_bf16_f32 v7, v18, v19
	s_waitcnt lgkmcnt(1)
	v_mfma_f32_32x32x16_bf16 v[112:127], v[2:5], v[144:147], v[112:127]
	ds_read_b128 v[14:17], v0 offset:160
	ds_read_b128 v[80:83], v0 offset:6816
	v_add_f32_e32 v0, v21, v8
	v_add_f32_e32 v0, v22, v0
	v_add_f32_e32 v0, v23, v0
	v_cvt_pk_bf16_f32 v8, v20, v21
	v_cvt_pk_bf16_f32 v9, v22, v23
	s_waitcnt lgkmcnt(2)
	v_mfma_f32_32x32x16_bf16 v[96:111], v[206:209], v[144:147], v[96:111]
	v_add_f32_e32 v0, v24, v0
	v_add_f32_e32 v0, v25, v0
	v_cvt_pk_bf16_f32 v2, v24, v25
	s_waitcnt lgkmcnt(1)
	v_mfma_f32_32x32x16_bf16 v[112:127], v[14:17], v[148:151], v[112:127]
	v_add_f32_e32 v0, v26, v0
	v_add_f32_e32 v0, v27, v0
	v_add_f32_e32 v0, v28, v0
	v_cvt_pk_bf16_f32 v3, v26, v27
	s_waitcnt lgkmcnt(0)
	v_mfma_f32_32x32x16_bf16 v[96:111], v[80:83], v[148:151], v[96:111]
	v_add_f32_e32 v0, v29, v0
	v_add_f32_e32 v0, v30, v0
	v_add_f32_e32 v0, v31, v0
	v_cvt_pk_bf16_f32 v4, v28, v29
	v_cvt_pk_bf16_f32 v5, v30, v31
	s_mul_i32 s4, s69, 0x2400
	v_add_u32_e32 v206, s4, v200
	ds_read_b128 v[16:19], v206 offset:53248
	ds_read_b128 v[202:205], v206 offset:57856
	s_cmp_ge_i32 s70, s65
	v_add_f32_e32 v201, v201, v0
	s_cbranch_scc1 .LBB0_693
	s_cmp_le_i32 s68, s63
	s_cbranch_scc0 .Latt_mask1
